# attention main loops: fold m0 setup into s_add_i32 m0 / drop s_nop via reordering (24 instrs) + 3 trivially-satisfied waits removed
# baseline (speedup 1.0000x reference)
;   #define RSCALE(t) do{ if(HAS_BIAS&&((t)==tn0||(t)==tn1)){ const float f_=__builtin_amdgcn_exp2f(CREG((t)-1)-CREG(t)); l_reg*=f_; \
;     _Pragma("unroll") for(int d_=0;d_<2*VH;++d_) _Pragma("unroll") for(int r=0;r<16;++r)o[d_][r]*=f_; } }while(0)
;   #define ROT() do{sv_prev=sv_cur;sv_cur=sv_next;sv_next=(sv_next==2*VSL)?0:sv_next+VSL;}while(0)
;   #define WAITFULL() do{ if(VH==1){WAIT_BAR(2);}else{WAIT_BAR(3);} }while(0)
; template<int VH,bool HAS_BIAS,int MODE> __device__ __forceinline__ void attn_unit2(const bf16*Qb,int qp,const bf16*__restrict__ Kb,int kp,const bf16*__restrict__ Vb,int vp,bf16*Ob,int op,int q0,int NT,const float*relb,char*shm,float lam,const float*subg,float gmul){
;     ...
;   int t=1;
;   for(;t+5<NT;t+=2){
;     STEP(pB0,pB1,pA0,pA1,t,true,true,true);     WAITFULL(); RSCALE(t);   ROT();
.LBB0_615:
	s_mov_b32 s62, s60
	s_mov_b32 s60, s56
	s_mov_b32 s58, s66
	s_mov_b64 s[22:23], s[44:45]
	s_mov_b32 s59, s65
	v_add_u32_e32 v148, s64, v167
	ds_read_b64_tr_b16 v[140:141], v148 offset:32768
	ds_read_b64_tr_b16 v[142:143], v148 offset:33280
	s_add_i32 s14, s63, 0xffffe000
	s_and_b32 s44, s14, 0x6000
	v_add_u32_e32 v96, s44, v164
	s_waitcnt lgkmcnt(2)
	v_mfma_f32_32x32x16_bf16 v[80:95], v[80:83], v[124:127], 0
	v_add_f32_e32 v64, v48, v49
	v_add_f32_e32 v64, v50, v64
	v_add_f32_e32 v64, v51, v64
	v_add_f32_e32 v64, v52, v64
	v_add_f32_e32 v64, v53, v64
	v_cvt_pk_bf16_f32 v108, v48, v49
	v_cvt_pk_bf16_f32 v109, v50, v51
	ds_read_b64_tr_b16 v[48:49], v148 offset:36864
	ds_read_b64_tr_b16 v[50:51], v148 offset:37376
	v_add_f32_e32 v64, v54, v64
	v_add_f32_e32 v64, v55, v64
	v_add_f32_e32 v64, v56, v64
	v_add_f32_e32 v97, v57, v64
	v_cvt_pk_bf16_f32 v110, v52, v53
	v_cvt_pk_bf16_f32 v111, v54, v55
	v_mfma_f32_32x32x16_bf16 v[64:79], v[136:139], v[124:127], 0
	ds_read_b128 v[52:55], v96 offset:4096
	ds_read_b128 v[136:139], v96 offset:4608
	ds_read_b64_tr_b16 v[144:145], v148 offset:33792
	ds_read_b64_tr_b16 v[146:147], v148 offset:34304
	v_mfma_f32_32x32x16_bf16 v[80:95], v[132:135], v[120:123], v[80:95]
	v_add_f32_e32 v97, v58, v97
	v_add_f32_e32 v97, v59, v97
	v_add_f32_e32 v97, v60, v97
	v_add_f32_e32 v97, v61, v97
	v_cvt_pk_bf16_f32 v104, v56, v57
	v_cvt_pk_bf16_f32 v105, v58, v59
	ds_read_b64_tr_b16 v[56:57], v148 offset:37888
	ds_read_b64_tr_b16 v[58:59], v148 offset:38400
	v_add_f32_e32 v97, v62, v97
	v_add_f32_e32 v97, v63, v97
	v_add_f32_e32 v97, v32, v97
	v_add_f32_e32 v97, v33, v97
	v_cvt_pk_bf16_f32 v106, v60, v61
	v_cvt_pk_bf16_f32 v107, v62, v63
	v_mfma_f32_32x32x16_bf16 v[64:79], v[128:131], v[120:123], v[64:79]
	ds_read_b128 v[60:63], v96 offset:6144
	ds_read_b128 v[128:131], v96 offset:6656
	ds_read_b64_tr_b16 v[132:133], v148 offset:34816
	ds_read_b64_tr_b16 v[134:135], v148 offset:35328
	s_waitcnt lgkmcnt(9)
	v_mfma_f32_32x32x16_bf16 v[80:95], v[52:55], v[116:119], v[80:95]
	v_add_f32_e32 v96, v34, v97
	v_add_f32_e32 v96, v35, v96
	v_add_f32_e32 v96, v36, v96
	v_add_f32_e32 v96, v37, v96
	v_cvt_pk_bf16_f32 v100, v32, v33
	v_cvt_pk_bf16_f32 v101, v34, v35
	ds_read_b64_tr_b16 v[32:33], v148 offset:38912
	ds_read_b64_tr_b16 v[34:35], v148 offset:39424
	v_add_f32_e32 v52, v38, v96
	v_add_f32_e32 v52, v39, v52
	v_add_f32_e32 v52, v40, v52
	v_add_f32_e32 v52, v41, v52
	v_cvt_pk_bf16_f32 v102, v36, v37
	v_cvt_pk_bf16_f32 v103, v38, v39
	s_waitcnt lgkmcnt(10)
	v_mfma_f32_32x32x16_bf16 v[64:79], v[136:139], v[116:119], v[64:79]
	ds_read_b64_tr_b16 v[36:37], v148 offset:35840
	ds_read_b64_tr_b16 v[38:39], v148 offset:36352
	s_waitcnt lgkmcnt(7)
	v_mfma_f32_32x32x16_bf16 v[80:95], v[60:63], v[112:115], v[80:95]
	v_add_f32_e32 v52, v42, v52
	v_add_f32_e32 v52, v43, v52
	v_add_f32_e32 v52, v44, v52
	v_add_f32_e32 v52, v45, v52
	v_cvt_pk_bf16_f32 v96, v40, v41
	v_cvt_pk_bf16_f32 v97, v42, v43
	ds_read_b64_tr_b16 v[40:41], v148 offset:39936
	ds_read_b64_tr_b16 v[42:43], v148 offset:40448
	v_add_f32_e32 v52, v46, v52
	v_add_f32_e32 v52, v47, v52
	v_add_f32_e32 v52, 0, v52
	v_cvt_pk_bf16_f32 v98, v44, v45
	v_cvt_pk_bf16_f32 v99, v46, v47
	s_waitcnt lgkmcnt(8)
	v_mfma_f32_32x32x16_bf16 v[64:79], v[128:131], v[112:115], v[64:79]
	s_add_i32 s64, s63, 0x4000
	s_and_b32 s14, s64, 0x6000
	s_add_i32 m0, s14, s54
	s_add_u32 s34, s42, 0xffff8000
	s_addc_u32 s35, s43, -1
	global_load_lds_dwordx4 v169, s[34:35]
	s_add_i32 m0, s62, s55
	s_add_u32 s34, s40, 0xffff8000
	s_addc_u32 s35, s41, -1
	global_load_lds_dwordx4 v170, s[34:35]
	v_add_f32_e32 v148, v168, v52
	v_mfma_f32_32x32x16_bf16 v[0:15], v[108:111], v[140:143], v[0:15]
	v_exp_f32_e32 v80, v80
	v_exp_f32_e32 v81, v81
	v_exp_f32_e32 v82, v82
	v_exp_f32_e32 v83, v83
	v_mfma_f32_32x32x16_bf16 v[16:31], v[108:111], v[48:51], v[16:31]
	v_exp_f32_e32 v84, v84
	v_exp_f32_e32 v85, v85
	v_exp_f32_e32 v86, v86
	v_exp_f32_e32 v87, v87
	v_mfma_f32_32x32x16_bf16 v[0:15], v[104:107], v[144:147], v[0:15]
	v_exp_f32_e32 v88, v88
	v_exp_f32_e32 v89, v89
	v_exp_f32_e32 v90, v90
	v_exp_f32_e32 v91, v91
	v_mfma_f32_32x32x16_bf16 v[16:31], v[104:107], v[56:59], v[16:31]
	v_exp_f32_e32 v92, v92
	v_exp_f32_e32 v93, v93
	v_exp_f32_e32 v94, v94
	v_exp_f32_e32 v95, v95
	s_and_b32 s14, s63, 0x6000
	v_add_u32_e32 v149, s14, v164
	ds_read_b128 v[44:47], v149
	ds_read_b128 v[128:131], v149 offset:512
	ds_read_b128 v[136:139], v149 offset:2048
	ds_read_b128 v[140:143], v149 offset:2560
	s_waitcnt lgkmcnt(10)
	v_mfma_f32_32x32x16_bf16 v[0:15], v[100:103], v[132:135], v[0:15]
	v_exp_f32_e32 v64, v64
	v_exp_f32_e32 v65, v65
	v_exp_f32_e32 v66, v66
	v_exp_f32_e32 v67, v67
	s_waitcnt lgkmcnt(8)
	v_mfma_f32_32x32x16_bf16 v[16:31], v[100:103], v[32:35], v[16:31]
	v_exp_f32_e32 v68, v68
	v_exp_f32_e32 v69, v69
	v_exp_f32_e32 v70, v70
	v_exp_f32_e32 v71, v71
	s_waitcnt lgkmcnt(6)
	v_mfma_f32_32x32x16_bf16 v[0:15], v[96:99], v[36:39], v[0:15]
	v_exp_f32_e32 v72, v72
	v_exp_f32_e32 v73, v73
	v_exp_f32_e32 v74, v74
	v_exp_f32_e32 v75, v75
	s_waitcnt lgkmcnt(4)
	v_mfma_f32_32x32x16_bf16 v[16:31], v[96:99], v[40:43], v[16:31]
	v_exp_f32_e32 v76, v76
	v_exp_f32_e32 v77, v77
	v_exp_f32_e32 v78, v78
	v_exp_f32_e32 v79, v79
	s_waitcnt vmcnt(2) lgkmcnt(0)
	s_barrier
;   #define RSCALE(t) do{ if(HAS_BIAS&&((t)==tn0||(t)==tn1)){ const float f_=__builtin_amdgcn_exp2f(CREG((t)-1)-CREG(t)); l_reg*=f_; \
;     _Pragma("unroll") for(int d_=0;d_<2*VH;++d_) _Pragma("unroll") for(int r=0;r<16;++r)o[d_][r]*=f_; } }while(0)
;   #define ROT() do{sv_prev=sv_cur;sv_cur=sv_next;sv_next=(sv_next==2*VSL)?0:sv_next+VSL;}while(0)
;   #define WAITFULL() do{ if(VH==1){WAIT_BAR(2);}else{WAIT_BAR(3);} }while(0)
; template<int VH,bool HAS_BIAS,int MODE> __device__ __forceinline__ void attn_unit2(const bf16*Qb,int qp,const bf16*__restrict__ Kb,int kp,const bf16*__restrict__ Vb,int vp,bf16*Ob,int op,int q0,int NT,const float*relb,char*shm,float lam,const float*subg,float gmul){
;     ...
;   int t=1;
;   for(;t+5<NT;t+=2){
;     STEP(pB0,pB1,pA0,pA1,t,true,true,true);     WAITFULL(); RSCALE(t);   ROT();
;     STEP(pA0,pA1,pB0,pB1,t+1,true,true,true);   WAITFULL(); RSCALE(t+1); ROT();
	s_add_i32 s14, s62, 0x2000
	s_cmpk_lg_i32 s62, 0x4000
	s_cselect_b32 s56, s14, 0
	v_add_u32_e32 v150, s60, v167
	ds_read_b64_tr_b16 v[132:133], v150 offset:32768
	ds_read_b64_tr_b16 v[134:135], v150 offset:33280
	v_mfma_f32_32x32x16_bf16 v[48:63], v[44:47], v[124:127], 0
	v_add_f32_e32 v32, v80, v81
	v_add_f32_e32 v32, v82, v32
	v_add_f32_e32 v32, v83, v32
	v_add_f32_e32 v32, v84, v32
	v_add_f32_e32 v32, v85, v32
	v_cvt_pk_bf16_f32 v108, v80, v81
	v_cvt_pk_bf16_f32 v109, v82, v83
	ds_read_b64_tr_b16 v[80:81], v150 offset:36864
	ds_read_b64_tr_b16 v[82:83], v150 offset:37376
	v_add_f32_e32 v32, v86, v32
	v_add_f32_e32 v32, v87, v32
	v_add_f32_e32 v32, v88, v32
	v_add_f32_e32 v96, v89, v32
	s_waitcnt lgkmcnt(6)
	v_mfma_f32_32x32x16_bf16 v[32:47], v[128:131], v[124:127], 0
	v_cvt_pk_bf16_f32 v110, v84, v85
	v_cvt_pk_bf16_f32 v111, v86, v87
	ds_read_b128 v[84:87], v149 offset:4096
	ds_read_b128 v[128:131], v149 offset:4608
	ds_read_b64_tr_b16 v[144:145], v150 offset:33792
	ds_read_b64_tr_b16 v[146:147], v150 offset:34304
	s_waitcnt lgkmcnt(9)
	v_mfma_f32_32x32x16_bf16 v[48:63], v[136:139], v[120:123], v[48:63]
	v_add_f32_e32 v96, v90, v96
	v_add_f32_e32 v96, v91, v96
	v_add_f32_e32 v96, v92, v96
	v_add_f32_e32 v96, v93, v96
	v_cvt_pk_bf16_f32 v104, v88, v89
	v_cvt_pk_bf16_f32 v105, v90, v91
	ds_read_b64_tr_b16 v[88:89], v150 offset:37888
	ds_read_b64_tr_b16 v[90:91], v150 offset:38400
	s_waitcnt lgkmcnt(10)
	v_mfma_f32_32x32x16_bf16 v[32:47], v[140:143], v[120:123], v[32:47]
	v_add_f32_e32 v96, v94, v96
	v_add_f32_e32 v96, v95, v96
	v_add_f32_e32 v96, v64, v96
	v_add_f32_e32 v96, v65, v96
	v_cvt_pk_bf16_f32 v106, v92, v93
	v_cvt_pk_bf16_f32 v107, v94, v95
	ds_read_b128 v[92:95], v149 offset:6144
	ds_read_b128 v[136:139], v149 offset:6656
	ds_read_b64_tr_b16 v[140:141], v150 offset:34816
	ds_read_b64_tr_b16 v[142:143], v150 offset:35328
	s_waitcnt lgkmcnt(9)
	v_mfma_f32_32x32x16_bf16 v[48:63], v[84:87], v[116:119], v[48:63]
	v_add_f32_e32 v96, v66, v96
	v_add_f32_e32 v96, v67, v96
	v_add_f32_e32 v96, v68, v96
	v_add_f32_e32 v96, v69, v96
	v_cvt_pk_bf16_f32 v100, v64, v65
	v_cvt_pk_bf16_f32 v101, v66, v67
	ds_read_b64_tr_b16 v[64:65], v150 offset:38912
	ds_read_b64_tr_b16 v[66:67], v150 offset:39424
	s_waitcnt lgkmcnt(10)
	v_mfma_f32_32x32x16_bf16 v[32:47], v[128:131], v[116:119], v[32:47]
	v_add_f32_e32 v84, v70, v96
	v_add_f32_e32 v84, v71, v84
	v_add_f32_e32 v84, v72, v84
	v_add_f32_e32 v84, v73, v84
	v_cvt_pk_bf16_f32 v102, v68, v69
	v_cvt_pk_bf16_f32 v103, v70, v71
	ds_read_b64_tr_b16 v[68:69], v150 offset:35840
	ds_read_b64_tr_b16 v[70:71], v150 offset:36352
	s_waitcnt lgkmcnt(7)
	v_mfma_f32_32x32x16_bf16 v[48:63], v[92:95], v[112:115], v[48:63]
	v_add_f32_e32 v84, v74, v84
	v_add_f32_e32 v84, v75, v84
	v_add_f32_e32 v84, v76, v84
	v_add_f32_e32 v84, v77, v84
	v_cvt_pk_bf16_f32 v96, v72, v73
	v_cvt_pk_bf16_f32 v97, v74, v75
	ds_read_b64_tr_b16 v[72:73], v150 offset:39936
	ds_read_b64_tr_b16 v[74:75], v150 offset:40448
	s_waitcnt lgkmcnt(8)
	v_mfma_f32_32x32x16_bf16 v[32:47], v[136:139], v[112:115], v[32:47]
	v_add_f32_e32 v84, v78, v84
	v_add_f32_e32 v84, v79, v84
	v_add_f32_e32 v84, 0, v84
	v_cvt_pk_bf16_f32 v98, v76, v77
	v_cvt_pk_bf16_f32 v99, v78, v79
	s_add_i32 m0, s44, s54
	s_add_i32 s57, s57, 2
	global_load_lds_dwordx4 v169, s[42:43]
	s_add_i32 m0, s56, s55
	v_add_f32_e32 v168, v148, v84
	global_load_lds_dwordx4 v170, s[40:41]
	v_mfma_f32_32x32x16_bf16 v[0:15], v[108:111], v[132:135], v[0:15]
	v_exp_f32_e32 v48, v48
	v_exp_f32_e32 v49, v49
	v_exp_f32_e32 v50, v50
	v_exp_f32_e32 v51, v51
	v_mfma_f32_32x32x16_bf16 v[16:31], v[108:111], v[80:83], v[16:31]
	v_exp_f32_e32 v52, v52
	v_exp_f32_e32 v53, v53
	v_exp_f32_e32 v54, v54
	v_exp_f32_e32 v55, v55
	v_mfma_f32_32x32x16_bf16 v[0:15], v[104:107], v[144:147], v[0:15]
	v_exp_f32_e32 v56, v56
	v_exp_f32_e32 v57, v57
	v_exp_f32_e32 v58, v58
	v_exp_f32_e32 v59, v59
	v_mfma_f32_32x32x16_bf16 v[16:31], v[104:107], v[88:91], v[16:31]
	v_exp_f32_e32 v60, v60
	v_exp_f32_e32 v61, v61
	v_exp_f32_e32 v62, v62
	v_exp_f32_e32 v63, v63
	s_add_i32 s14, s63, 0x2000
	s_and_b32 s14, s14, 0x6000
	v_add_u32_e32 v76, s14, v164
	ds_read_b128 v[80:83], v76
	ds_read_b128 v[136:139], v76 offset:512
	ds_read_b128 v[132:135], v76 offset:2048
	ds_read_b128 v[128:131], v76 offset:2560
	s_waitcnt lgkmcnt(10)
	v_mfma_f32_32x32x16_bf16 v[0:15], v[100:103], v[140:143], v[0:15]
	v_exp_f32_e32 v32, v32
	v_exp_f32_e32 v33, v33
	v_exp_f32_e32 v34, v34
	v_exp_f32_e32 v35, v35
	s_waitcnt lgkmcnt(8)
	v_mfma_f32_32x32x16_bf16 v[16:31], v[100:103], v[64:67], v[16:31]
	v_exp_f32_e32 v36, v36
	v_exp_f32_e32 v37, v37
	v_exp_f32_e32 v38, v38
	v_exp_f32_e32 v39, v39
	s_waitcnt lgkmcnt(6)
	v_mfma_f32_32x32x16_bf16 v[0:15], v[96:99], v[68:71], v[0:15]
	v_exp_f32_e32 v40, v40
	v_exp_f32_e32 v41, v41
	v_exp_f32_e32 v42, v42
	v_exp_f32_e32 v43, v43
	s_waitcnt lgkmcnt(4)
	v_mfma_f32_32x32x16_bf16 v[16:31], v[96:99], v[72:75], v[16:31]
	v_exp_f32_e32 v44, v44
	v_exp_f32_e32 v45, v45
	v_exp_f32_e32 v46, v46
	v_exp_f32_e32 v47, v47
	s_add_i32 s14, s56, 0x2000
	s_cmpk_lg_i32 s56, 0x4000
	s_cselect_b32 s60, s14, 0
	s_add_u32 s40, s40, 0x10000
	s_addc_u32 s41, s41, 0
	s_add_u32 s42, s42, 0x10000
	s_addc_u32 s43, s43, 0
	s_addk_i32 s66, 0x4000
	s_waitcnt vmcnt(2) lgkmcnt(0)
	s_barrier
	s_add_u32 s44, s22, 0x10000
	s_addc_u32 s45, s23, 0
	s_add_i32 s65, s65, 2
	s_cmp_ge_u32 s57, s61
	s_mov_b32 s63, s64
	s_mov_b32 s64, s62
	s_cbranch_scc0 .LBB0_615
	s_add_i32 s14, s57, 1
	s_cmp_ge_u32 s14, s53
	s_cbranch_scc1 .LBB0_644
	s_add_i32 s61, s53, -2

.LBB0_1088:
	v_add_u32_e32 v0, s6, v204
	ds_read_b64_tr_b16 v[174:175], v0 offset:32768
	ds_read_b64_tr_b16 v[176:177], v0 offset:33280
	s_add_i32 s6, s42, 0xffffe000
	s_and_b32 s54, s6, 0x6000
	v_add_u32_e32 v130, s54, v201
	s_waitcnt lgkmcnt(2)
	v_mfma_f32_32x32x16_bf16 v[114:129], v[114:117], v[158:161], 0
	v_add_f32_e32 v98, v82, v83
	v_add_f32_e32 v98, v84, v98
	v_add_f32_e32 v98, v85, v98
	v_add_f32_e32 v98, v86, v98
	v_add_f32_e32 v98, v87, v98
	v_cvt_pk_bf16_f32 v142, v82, v83
	v_cvt_pk_bf16_f32 v143, v84, v85
	ds_read_b64_tr_b16 v[82:83], v0 offset:36864
	ds_read_b64_tr_b16 v[84:85], v0 offset:37376
	v_add_f32_e32 v98, v88, v98
	v_add_f32_e32 v98, v89, v98
	v_add_f32_e32 v98, v90, v98
	v_add_f32_e32 v131, v91, v98
	v_mfma_f32_32x32x16_bf16 v[98:113], v[170:173], v[158:161], 0
	v_cvt_pk_bf16_f32 v144, v86, v87
	v_cvt_pk_bf16_f32 v145, v88, v89
	ds_read_b128 v[170:173], v130 offset:4096
	ds_read_b128 v[206:209], v130 offset:4608
	ds_read_b64_tr_b16 v[86:87], v0 offset:33792
	ds_read_b64_tr_b16 v[88:89], v0 offset:34304
	v_mfma_f32_32x32x16_bf16 v[114:129], v[166:169], v[154:157], v[114:129]
	v_add_f32_e32 v131, v92, v131
	v_add_f32_e32 v131, v93, v131
	v_add_f32_e32 v131, v94, v131
	v_add_f32_e32 v131, v95, v131
	v_cvt_pk_bf16_f32 v138, v90, v91
	v_cvt_pk_bf16_f32 v139, v92, v93
	ds_read_b64_tr_b16 v[90:91], v0 offset:37888
	ds_read_b64_tr_b16 v[92:93], v0 offset:38400
	v_mfma_f32_32x32x16_bf16 v[98:113], v[162:165], v[154:157], v[98:113]
	v_add_f32_e32 v131, v96, v131
	v_add_f32_e32 v131, v97, v131
	v_add_f32_e32 v131, v66, v131
	v_add_f32_e32 v131, v67, v131
	v_cvt_pk_bf16_f32 v140, v94, v95
	v_cvt_pk_bf16_f32 v141, v96, v97
	ds_read_b128 v[162:165], v130 offset:6144
	ds_read_b128 v[166:169], v130 offset:6656
	ds_read_b64_tr_b16 v[94:95], v0 offset:34816
	ds_read_b64_tr_b16 v[96:97], v0 offset:35328
	s_waitcnt lgkmcnt(9)
	v_mfma_f32_32x32x16_bf16 v[114:129], v[170:173], v[150:153], v[114:129]
	v_add_f32_e32 v130, v68, v131
	v_add_f32_e32 v130, v69, v130
	v_add_f32_e32 v130, v70, v130
	v_add_f32_e32 v130, v71, v130
	v_cvt_pk_bf16_f32 v134, v66, v67
	v_cvt_pk_bf16_f32 v135, v68, v69
	ds_read_b64_tr_b16 v[66:67], v0 offset:38912
	ds_read_b64_tr_b16 v[68:69], v0 offset:39424
	s_waitcnt lgkmcnt(10)
	v_mfma_f32_32x32x16_bf16 v[98:113], v[206:209], v[150:153], v[98:113]
	v_add_f32_e32 v130, v72, v130
	v_add_f32_e32 v130, v73, v130
	v_add_f32_e32 v130, v74, v130
	v_add_f32_e32 v130, v75, v130
	v_cvt_pk_bf16_f32 v136, v70, v71
	v_cvt_pk_bf16_f32 v137, v72, v73
	ds_read_b64_tr_b16 v[70:71], v0 offset:35840
	ds_read_b64_tr_b16 v[72:73], v0 offset:36352
	s_waitcnt lgkmcnt(7)
	v_mfma_f32_32x32x16_bf16 v[114:129], v[162:165], v[146:149], v[114:129]
	v_add_f32_e32 v130, v76, v130
	v_add_f32_e32 v130, v77, v130
	v_add_f32_e32 v130, v78, v130
	v_add_f32_e32 v170, v79, v130
	v_cvt_pk_bf16_f32 v130, v74, v75
	v_cvt_pk_bf16_f32 v131, v76, v77
	ds_read_b64_tr_b16 v[74:75], v0 offset:39936
	ds_read_b64_tr_b16 v[76:77], v0 offset:40448
	s_waitcnt lgkmcnt(8)
	v_mfma_f32_32x32x16_bf16 v[98:113], v[166:169], v[146:149], v[98:113]
	v_add_f32_e32 v132, v80, v170
	v_add_f32_e32 v132, v81, v132
	v_add_f32_e32 v162, 0, v132
	v_cvt_pk_bf16_f32 v132, v78, v79
	v_cvt_pk_bf16_f32 v133, v80, v81
	s_add_u32 s87, s44, s8
	s_addc_u32 s88, s45, s9
	s_add_u32 s6, s87, 0x80000
	s_addc_u32 s7, s88, 0
	s_add_i32 s16, s42, 0x4000
	s_and_b32 s12, s16, 0x6000
	s_add_i32 m0, s12, s33
	s_add_u32 s85, s71, s8
	s_addc_u32 s86, s73, s9
	global_load_lds_dwordx4 v202, s[6:7]
	s_add_u32 s6, s85, 0x22040000
	s_addc_u32 s7, s86, 0
	s_add_i32 s12, s11, s59
	s_mov_b32 m0, s12
	s_add_u32 s90, s85, 0x22040080
	global_load_lds_dwordx4 v203, s[6:7]
	s_addc_u32 s91, s86, 0
	s_addk_i32 s12, 0x2000
	s_mov_b32 m0, s12
	s_cmp_ge_i32 s10, s57
	s_cselect_b64 s[92:93], -1, 0
	s_cmp_gt_i32 s58, s10
	s_cselect_b64 s[6:7], -1, 0
	global_load_lds_dwordx4 v203, s[90:91]
	s_and_b64 s[92:93], s[92:93], s[6:7]
	s_andn2_b64 vcc, exec, s[92:93]
	s_cbranch_vccnz .LBB0_1090
	ds_read2_b32 v[78:79], v179 offset1:1
	ds_read2_b32 v[80:81], v179 offset0:2 offset1:3
	ds_read2_b32 v[164:165], v179 offset0:8 offset1:9
	ds_read2_b32 v[166:167], v179 offset0:10 offset1:11
	ds_read2_b32 v[168:169], v179 offset0:16 offset1:17
	ds_read2_b32 v[170:171], v179 offset0:18 offset1:19
	ds_read2_b32 v[172:173], v179 offset0:24 offset1:25
	ds_read2_b32 v[180:181], v179 offset0:26 offset1:27
	ds_read2_b32 v[206:207], v179 offset0:32 offset1:33
	ds_read2_b32 v[208:209], v179 offset0:34 offset1:35
	ds_read2_b32 v[210:211], v179 offset0:40 offset1:41
	ds_read2_b32 v[212:213], v179 offset0:42 offset1:43
	s_waitcnt lgkmcnt(11)
	v_pk_add_f32 v[114:115], v[114:115], v[78:79]
	s_waitcnt lgkmcnt(5)
	v_pk_add_f32 v[126:127], v[126:127], v[172:173]
	v_pk_add_f32 v[124:125], v[124:125], v[170:171]
	v_pk_add_f32 v[122:123], v[122:123], v[168:169]
	ds_read2_b32 v[78:79], v179 offset0:48 offset1:49
	ds_read2_b32 v[168:169], v179 offset0:50 offset1:51
	ds_read2_b32 v[170:171], v179 offset0:56 offset1:57
	ds_read2_b32 v[172:173], v179 offset0:58 offset1:59
	s_waitcnt lgkmcnt(8)
	v_pk_add_f32 v[128:129], v[128:129], v[180:181]
	v_pk_add_f32 v[120:121], v[120:121], v[166:167]
	v_pk_add_f32 v[118:119], v[118:119], v[164:165]
	v_pk_add_f32 v[116:117], v[116:117], v[80:81]
	s_waitcnt lgkmcnt(7)
	v_pk_add_f32 v[98:99], v[98:99], v[206:207]
	s_waitcnt lgkmcnt(0)
	v_pk_add_f32 v[112:113], v[112:113], v[172:173]
	v_pk_add_f32 v[110:111], v[110:111], v[170:171]
	v_pk_add_f32 v[108:109], v[108:109], v[168:169]
	v_pk_add_f32 v[106:107], v[106:107], v[78:79]
	v_pk_add_f32 v[104:105], v[104:105], v[212:213]
	v_pk_add_f32 v[102:103], v[102:103], v[210:211]
	v_pk_add_f32 v[100:101], v[100:101], v[208:209]

.LBB0_1092:
	s_add_i32 s89, s10, 1
	s_add_i32 s6, s11, 0x4000
	s_cmpk_lg_u32 s11, 0x8000
	s_cselect_b32 s83, s6, 0
	v_add_u32_e32 v174, s55, v204
	ds_read_b64_tr_b16 v[170:171], v174 offset:32768
	ds_read_b64_tr_b16 v[172:173], v174 offset:33280
	v_mfma_f32_32x32x16_bf16 v[82:97], v[70:73], v[158:161], 0
	v_add_f32_e32 v74, v114, v115
	v_add_f32_e32 v74, v116, v74
	v_add_f32_e32 v74, v117, v74
	v_add_f32_e32 v74, v118, v74
	v_add_f32_e32 v74, v119, v74
	v_cvt_pk_bf16_f32 v142, v114, v115
	v_cvt_pk_bf16_f32 v143, v116, v117
	ds_read_b64_tr_b16 v[114:115], v174 offset:36864
	ds_read_b64_tr_b16 v[116:117], v174 offset:37376
	v_add_f32_e32 v70, v120, v74
	v_add_f32_e32 v70, v121, v70
	v_add_f32_e32 v70, v122, v70
	v_add_f32_e32 v130, v123, v70
	s_waitcnt lgkmcnt(6)
	v_mfma_f32_32x32x16_bf16 v[66:81], v[66:69], v[158:161], 0
	v_cvt_pk_bf16_f32 v144, v118, v119
	v_cvt_pk_bf16_f32 v145, v120, v121
	ds_read_b128 v[206:209], v175 offset:4096
	ds_read_b128 v[210:213], v175 offset:4608
	ds_read_b64_tr_b16 v[118:119], v174 offset:33792
	ds_read_b64_tr_b16 v[120:121], v174 offset:34304
	s_waitcnt lgkmcnt(9)
	v_mfma_f32_32x32x16_bf16 v[82:97], v[166:169], v[154:157], v[82:97]
	v_add_f32_e32 v130, v124, v130
	v_add_f32_e32 v130, v125, v130
	v_add_f32_e32 v130, v126, v130
	v_add_f32_e32 v130, v127, v130
	v_cvt_pk_bf16_f32 v138, v122, v123
	v_cvt_pk_bf16_f32 v139, v124, v125
	ds_read_b64_tr_b16 v[122:123], v174 offset:37888
	ds_read_b64_tr_b16 v[124:125], v174 offset:38400
	s_waitcnt lgkmcnt(10)
	v_mfma_f32_32x32x16_bf16 v[66:81], v[162:165], v[154:157], v[66:81]
	v_add_f32_e32 v130, v128, v130
	v_add_f32_e32 v130, v129, v130
	v_add_f32_e32 v130, v98, v130
	v_add_f32_e32 v130, v99, v130
	v_cvt_pk_bf16_f32 v140, v126, v127
	v_cvt_pk_bf16_f32 v141, v128, v129
	ds_read_b128 v[162:165], v175 offset:6144
	ds_read_b128 v[166:169], v175 offset:6656
	ds_read_b64_tr_b16 v[126:127], v174 offset:34816
	ds_read_b64_tr_b16 v[128:129], v174 offset:35328
	s_waitcnt lgkmcnt(9)
	v_mfma_f32_32x32x16_bf16 v[82:97], v[206:209], v[150:153], v[82:97]
	v_add_f32_e32 v130, v100, v130
	v_add_f32_e32 v130, v101, v130
	v_add_f32_e32 v130, v102, v130
	v_add_f32_e32 v130, v103, v130
	v_cvt_pk_bf16_f32 v134, v98, v99
	v_cvt_pk_bf16_f32 v135, v100, v101
	ds_read_b64_tr_b16 v[98:99], v174 offset:38912
	ds_read_b64_tr_b16 v[100:101], v174 offset:39424
	s_waitcnt lgkmcnt(10)
	v_mfma_f32_32x32x16_bf16 v[66:81], v[210:213], v[150:153], v[66:81]
	v_add_f32_e32 v130, v104, v130
	v_add_f32_e32 v130, v105, v130
	v_add_f32_e32 v130, v106, v130
	v_add_f32_e32 v130, v107, v130
	v_cvt_pk_bf16_f32 v136, v102, v103
	v_cvt_pk_bf16_f32 v137, v104, v105
	ds_read_b64_tr_b16 v[102:103], v174 offset:35840
	ds_read_b64_tr_b16 v[104:105], v174 offset:36352
	s_waitcnt lgkmcnt(7)
	v_mfma_f32_32x32x16_bf16 v[82:97], v[162:165], v[146:149], v[82:97]
	v_add_f32_e32 v130, v108, v130
	v_add_f32_e32 v130, v109, v130
	v_add_f32_e32 v130, v110, v130
	v_add_f32_e32 v175, v111, v130
	v_cvt_pk_bf16_f32 v130, v106, v107
	v_cvt_pk_bf16_f32 v131, v108, v109
	ds_read_b64_tr_b16 v[106:107], v174 offset:39936
	ds_read_b64_tr_b16 v[108:109], v174 offset:40448
	s_waitcnt lgkmcnt(8)
	v_mfma_f32_32x32x16_bf16 v[66:81], v[166:169], v[146:149], v[66:81]
	v_add_f32_e32 v132, v112, v175
	v_add_f32_e32 v132, v113, v132
	v_add_f32_e32 v162, 0, v132
	v_cvt_pk_bf16_f32 v132, v110, v111
	v_cvt_pk_bf16_f32 v133, v112, v113
	s_add_i32 m0, s54, s33
	s_add_u32 s6, s87, 0xa0000
	s_addc_u32 s7, s88, 0
	global_load_lds_dwordx4 v202, s[6:7]
	s_add_u32 s6, s85, 0x22060000
	s_addc_u32 s7, s86, 0
	s_add_i32 s12, s83, s59
	s_mov_b32 m0, s12
	s_add_u32 s54, s85, 0x22060080
	global_load_lds_dwordx4 v203, s[6:7]
	s_addc_u32 s55, s86, 0
	s_addk_i32 s12, 0x2000
	s_mov_b32 m0, s12
	s_cmp_ge_i32 s89, s57
	s_cselect_b64 s[86:87], -1, 0
	s_cmp_lt_i32 s89, s60
	s_cselect_b64 s[6:7], -1, 0
	global_load_lds_dwordx4 v203, s[54:55]
	s_and_b64 s[86:87], s[86:87], s[6:7]
	s_andn2_b64 vcc, exec, s[86:87]
	s_cbranch_vccnz .LBB0_1094
	ds_read2_b32 v[110:111], v179 offset0:64 offset1:65
	ds_read2_b32 v[112:113], v179 offset0:66 offset1:67
	ds_read2_b32 v[164:165], v179 offset0:72 offset1:73
	ds_read2_b32 v[166:167], v179 offset0:74 offset1:75
	ds_read2_b32 v[168:169], v179 offset0:80 offset1:81
	ds_read2_b32 v[176:177], v179 offset0:82 offset1:83
	ds_read2_b32 v[180:181], v179 offset0:88 offset1:89
	ds_read2_b32 v[206:207], v179 offset0:90 offset1:91
	ds_read2_b32 v[208:209], v179 offset0:96 offset1:97
	ds_read2_b32 v[210:211], v179 offset0:98 offset1:99
	ds_read2_b32 v[212:213], v179 offset0:104 offset1:105
	ds_read2_b32 v[214:215], v179 offset0:106 offset1:107
	s_waitcnt lgkmcnt(11)
	v_pk_add_f32 v[82:83], v[82:83], v[110:111]
	s_waitcnt lgkmcnt(5)
	v_pk_add_f32 v[94:95], v[94:95], v[180:181]
	v_pk_add_f32 v[92:93], v[92:93], v[176:177]
	v_pk_add_f32 v[90:91], v[90:91], v[168:169]
	ds_read2_b32 v[110:111], v179 offset0:112 offset1:113
	ds_read2_b32 v[168:169], v179 offset0:114 offset1:115
	ds_read2_b32 v[176:177], v179 offset0:120 offset1:121
	ds_read2_b32 v[180:181], v179 offset0:122 offset1:123
	s_waitcnt lgkmcnt(8)
	v_pk_add_f32 v[96:97], v[96:97], v[206:207]
	v_pk_add_f32 v[88:89], v[88:89], v[166:167]
	v_pk_add_f32 v[86:87], v[86:87], v[164:165]
	v_pk_add_f32 v[84:85], v[84:85], v[112:113]
	s_waitcnt lgkmcnt(7)
	v_pk_add_f32 v[66:67], v[66:67], v[208:209]
	s_waitcnt lgkmcnt(0)
	v_pk_add_f32 v[80:81], v[80:81], v[180:181]
	v_pk_add_f32 v[78:79], v[78:79], v[176:177]
	v_pk_add_f32 v[76:77], v[76:77], v[168:169]
	v_pk_add_f32 v[74:75], v[74:75], v[110:111]
	v_pk_add_f32 v[72:73], v[72:73], v[214:215]
	v_pk_add_f32 v[70:71], v[70:71], v[212:213]
	v_pk_add_f32 v[68:69], v[68:69], v[210:211]

.LBB0_1156:
	v_add_u32_e32 v0, s6, v208
	ds_read_b64_tr_b16 v[174:175], v0 offset:32768
	ds_read_b64_tr_b16 v[176:177], v0 offset:33280
	s_add_i32 s6, s47, 0xffffe000
	s_and_b32 s60, s6, 0x6000
	v_add_u32_e32 v130, s60, v205
	s_waitcnt lgkmcnt(2)
	v_mfma_f32_32x32x16_bf16 v[114:129], v[114:117], v[158:161], 0
	v_add_f32_e32 v98, v82, v83
	v_add_f32_e32 v98, v84, v98
	v_add_f32_e32 v98, v85, v98
	v_add_f32_e32 v98, v86, v98
	v_add_f32_e32 v98, v87, v98
	v_cvt_pk_bf16_f32 v142, v82, v83
	v_cvt_pk_bf16_f32 v143, v84, v85
	ds_read_b64_tr_b16 v[82:83], v0 offset:36864
	ds_read_b64_tr_b16 v[84:85], v0 offset:37376
	v_add_f32_e32 v98, v88, v98
	v_add_f32_e32 v98, v89, v98
	v_add_f32_e32 v98, v90, v98
	v_add_f32_e32 v131, v91, v98
	v_mfma_f32_32x32x16_bf16 v[98:113], v[170:173], v[158:161], 0
	v_cvt_pk_bf16_f32 v144, v86, v87
	v_cvt_pk_bf16_f32 v145, v88, v89
	ds_read_b128 v[170:173], v130 offset:4096
	ds_read_b128 v[210:213], v130 offset:4608
	ds_read_b64_tr_b16 v[86:87], v0 offset:33792
	ds_read_b64_tr_b16 v[88:89], v0 offset:34304
	v_mfma_f32_32x32x16_bf16 v[114:129], v[166:169], v[154:157], v[114:129]
	v_add_f32_e32 v131, v92, v131
	v_add_f32_e32 v131, v93, v131
	v_add_f32_e32 v131, v94, v131
	v_add_f32_e32 v131, v95, v131
	v_cvt_pk_bf16_f32 v138, v90, v91
	v_cvt_pk_bf16_f32 v139, v92, v93
	ds_read_b64_tr_b16 v[90:91], v0 offset:37888
	ds_read_b64_tr_b16 v[92:93], v0 offset:38400
	v_mfma_f32_32x32x16_bf16 v[98:113], v[162:165], v[154:157], v[98:113]
	v_add_f32_e32 v131, v96, v131
	v_add_f32_e32 v131, v97, v131
	v_add_f32_e32 v131, v66, v131
	v_add_f32_e32 v131, v67, v131
	v_cvt_pk_bf16_f32 v140, v94, v95
	v_cvt_pk_bf16_f32 v141, v96, v97
	ds_read_b128 v[162:165], v130 offset:6144
	ds_read_b128 v[166:169], v130 offset:6656
	ds_read_b64_tr_b16 v[94:95], v0 offset:34816
	ds_read_b64_tr_b16 v[96:97], v0 offset:35328
	s_waitcnt lgkmcnt(9)
	v_mfma_f32_32x32x16_bf16 v[114:129], v[170:173], v[150:153], v[114:129]
	v_add_f32_e32 v130, v68, v131
	v_add_f32_e32 v130, v69, v130
	v_add_f32_e32 v130, v70, v130
	v_add_f32_e32 v130, v71, v130
	v_cvt_pk_bf16_f32 v134, v66, v67
	v_cvt_pk_bf16_f32 v135, v68, v69
	ds_read_b64_tr_b16 v[66:67], v0 offset:38912
	ds_read_b64_tr_b16 v[68:69], v0 offset:39424
	s_waitcnt lgkmcnt(10)
	v_mfma_f32_32x32x16_bf16 v[98:113], v[210:213], v[150:153], v[98:113]
	v_add_f32_e32 v130, v72, v130
	v_add_f32_e32 v130, v73, v130
	v_add_f32_e32 v130, v74, v130
	v_add_f32_e32 v130, v75, v130
	v_cvt_pk_bf16_f32 v136, v70, v71
	v_cvt_pk_bf16_f32 v137, v72, v73
	ds_read_b64_tr_b16 v[70:71], v0 offset:35840
	ds_read_b64_tr_b16 v[72:73], v0 offset:36352
	s_waitcnt lgkmcnt(7)
	v_mfma_f32_32x32x16_bf16 v[114:129], v[162:165], v[146:149], v[114:129]
	v_add_f32_e32 v130, v76, v130
	v_add_f32_e32 v130, v77, v130
	v_add_f32_e32 v130, v78, v130
	v_add_f32_e32 v170, v79, v130
	v_cvt_pk_bf16_f32 v130, v74, v75
	v_cvt_pk_bf16_f32 v131, v76, v77
	ds_read_b64_tr_b16 v[74:75], v0 offset:39936
	ds_read_b64_tr_b16 v[76:77], v0 offset:40448
	s_waitcnt lgkmcnt(8)
	v_mfma_f32_32x32x16_bf16 v[98:113], v[166:169], v[146:149], v[98:113]
	v_add_f32_e32 v132, v80, v170
	v_add_f32_e32 v132, v81, v132
	v_add_f32_e32 v162, 0, v132
	v_cvt_pk_bf16_f32 v132, v78, v79
	v_cvt_pk_bf16_f32 v133, v80, v81
	s_add_u32 s77, s8, s40
	s_addc_u32 s78, s9, s41
	s_add_u32 s6, s77, 0x80000
	s_addc_u32 s7, s78, 0
	s_add_i32 s46, s47, 0x4000
	s_and_b32 s12, s46, 0x6000
	s_add_i32 m0, s12, s33
	s_add_u32 s75, s71, s40
	s_addc_u32 s76, s73, s41
	global_load_lds_dwordx4 v206, s[6:7]
	s_add_i32 s14, s45, s57
	s_mov_b32 m0, s14
	s_add_u32 s6, s75, 0x22040000
	s_addc_u32 s7, s76, 0
	global_load_lds_dwordx4 v207, s[6:7]
	s_add_u32 s12, s75, 0x22040080
	s_addc_u32 s13, s76, 0
	s_addk_i32 s14, 0x2000
	s_mov_b32 m0, s14
	s_cmp_ge_i32 s44, s55
	s_cselect_b64 s[82:83], -1, 0
	s_cmp_gt_i32 s56, s44
	s_cselect_b64 s[6:7], -1, 0
	global_load_lds_dwordx4 v207, s[12:13]
	s_and_b64 s[82:83], s[82:83], s[6:7]
	s_andn2_b64 vcc, exec, s[82:83]
	s_cbranch_vccnz .LBB0_1158
	ds_read2_b32 v[78:79], v179 offset1:1
	ds_read2_b32 v[80:81], v179 offset0:2 offset1:3
	ds_read2_b32 v[164:165], v179 offset0:8 offset1:9
	ds_read2_b32 v[166:167], v179 offset0:10 offset1:11
	ds_read2_b32 v[168:169], v179 offset0:16 offset1:17
	ds_read2_b32 v[170:171], v179 offset0:18 offset1:19
	ds_read2_b32 v[172:173], v179 offset0:24 offset1:25
	ds_read2_b32 v[180:181], v179 offset0:26 offset1:27
	ds_read2_b32 v[210:211], v179 offset0:32 offset1:33
	ds_read2_b32 v[212:213], v179 offset0:34 offset1:35
	ds_read2_b32 v[214:215], v179 offset0:40 offset1:41
	ds_read2_b32 v[216:217], v179 offset0:42 offset1:43
	s_waitcnt lgkmcnt(11)
	v_pk_add_f32 v[114:115], v[114:115], v[78:79]
	s_waitcnt lgkmcnt(5)
	v_pk_add_f32 v[126:127], v[126:127], v[172:173]
	v_pk_add_f32 v[124:125], v[124:125], v[170:171]
	v_pk_add_f32 v[122:123], v[122:123], v[168:169]
	ds_read2_b32 v[78:79], v179 offset0:48 offset1:49
	ds_read2_b32 v[168:169], v179 offset0:50 offset1:51
	ds_read2_b32 v[170:171], v179 offset0:56 offset1:57
	ds_read2_b32 v[172:173], v179 offset0:58 offset1:59
	s_waitcnt lgkmcnt(8)
	v_pk_add_f32 v[128:129], v[128:129], v[180:181]
	v_pk_add_f32 v[120:121], v[120:121], v[166:167]
	v_pk_add_f32 v[118:119], v[118:119], v[164:165]
	v_pk_add_f32 v[116:117], v[116:117], v[80:81]
	s_waitcnt lgkmcnt(7)
	v_pk_add_f32 v[98:99], v[98:99], v[210:211]
	s_waitcnt lgkmcnt(0)
	v_pk_add_f32 v[112:113], v[112:113], v[172:173]
	v_pk_add_f32 v[110:111], v[110:111], v[170:171]
	v_pk_add_f32 v[108:109], v[108:109], v[168:169]
	v_pk_add_f32 v[106:107], v[106:107], v[78:79]
	v_pk_add_f32 v[104:105], v[104:105], v[216:217]
	v_pk_add_f32 v[102:103], v[102:103], v[214:215]
	v_pk_add_f32 v[100:101], v[100:101], v[212:213]

.LBB0_1160:
	s_add_i32 s79, s44, 1
	s_add_i32 s6, s45, 0x4000
	s_cmpk_lg_u32 s45, 0x8000
	s_cselect_b32 s53, s6, 0
	v_add_u32_e32 v174, s61, v208
	ds_read_b64_tr_b16 v[170:171], v174 offset:32768
	ds_read_b64_tr_b16 v[172:173], v174 offset:33280
	v_mfma_f32_32x32x16_bf16 v[82:97], v[70:73], v[158:161], 0
	v_add_f32_e32 v74, v114, v115
	v_add_f32_e32 v74, v116, v74
	v_add_f32_e32 v74, v117, v74
	v_add_f32_e32 v74, v118, v74
	v_add_f32_e32 v74, v119, v74
	v_cvt_pk_bf16_f32 v142, v114, v115
	v_cvt_pk_bf16_f32 v143, v116, v117
	ds_read_b64_tr_b16 v[114:115], v174 offset:36864
	ds_read_b64_tr_b16 v[116:117], v174 offset:37376
	v_add_f32_e32 v70, v120, v74
	v_add_f32_e32 v70, v121, v70
	v_add_f32_e32 v70, v122, v70
	v_add_f32_e32 v130, v123, v70
	s_waitcnt lgkmcnt(6)
	v_mfma_f32_32x32x16_bf16 v[66:81], v[66:69], v[158:161], 0
	v_cvt_pk_bf16_f32 v144, v118, v119
	v_cvt_pk_bf16_f32 v145, v120, v121
	ds_read_b128 v[210:213], v175 offset:4096
	ds_read_b128 v[214:217], v175 offset:4608
	ds_read_b64_tr_b16 v[118:119], v174 offset:33792
	ds_read_b64_tr_b16 v[120:121], v174 offset:34304
	s_waitcnt lgkmcnt(9)
	v_mfma_f32_32x32x16_bf16 v[82:97], v[166:169], v[154:157], v[82:97]
	v_add_f32_e32 v130, v124, v130
	v_add_f32_e32 v130, v125, v130
	v_add_f32_e32 v130, v126, v130
	v_add_f32_e32 v130, v127, v130
	v_cvt_pk_bf16_f32 v138, v122, v123
	v_cvt_pk_bf16_f32 v139, v124, v125
	ds_read_b64_tr_b16 v[122:123], v174 offset:37888
	ds_read_b64_tr_b16 v[124:125], v174 offset:38400
	s_waitcnt lgkmcnt(10)
	v_mfma_f32_32x32x16_bf16 v[66:81], v[162:165], v[154:157], v[66:81]
	v_add_f32_e32 v130, v128, v130
	v_add_f32_e32 v130, v129, v130
	v_add_f32_e32 v130, v98, v130
	v_add_f32_e32 v130, v99, v130
	v_cvt_pk_bf16_f32 v140, v126, v127
	v_cvt_pk_bf16_f32 v141, v128, v129
	ds_read_b128 v[162:165], v175 offset:6144
	ds_read_b128 v[166:169], v175 offset:6656
	ds_read_b64_tr_b16 v[126:127], v174 offset:34816
	ds_read_b64_tr_b16 v[128:129], v174 offset:35328
	s_waitcnt lgkmcnt(9)
	v_mfma_f32_32x32x16_bf16 v[82:97], v[210:213], v[150:153], v[82:97]
	v_add_f32_e32 v130, v100, v130
	v_add_f32_e32 v130, v101, v130
	v_add_f32_e32 v130, v102, v130
	v_add_f32_e32 v130, v103, v130
	v_cvt_pk_bf16_f32 v134, v98, v99
	v_cvt_pk_bf16_f32 v135, v100, v101
	ds_read_b64_tr_b16 v[98:99], v174 offset:38912
	ds_read_b64_tr_b16 v[100:101], v174 offset:39424
	s_waitcnt lgkmcnt(10)
	v_mfma_f32_32x32x16_bf16 v[66:81], v[214:217], v[150:153], v[66:81]
	v_add_f32_e32 v130, v104, v130
	v_add_f32_e32 v130, v105, v130
	v_add_f32_e32 v130, v106, v130
	v_add_f32_e32 v130, v107, v130
	v_cvt_pk_bf16_f32 v136, v102, v103
	v_cvt_pk_bf16_f32 v137, v104, v105
	ds_read_b64_tr_b16 v[102:103], v174 offset:35840
	ds_read_b64_tr_b16 v[104:105], v174 offset:36352
	s_waitcnt lgkmcnt(7)
	v_mfma_f32_32x32x16_bf16 v[82:97], v[162:165], v[146:149], v[82:97]
	v_add_f32_e32 v130, v108, v130
	v_add_f32_e32 v130, v109, v130
	v_add_f32_e32 v130, v110, v130
	v_add_f32_e32 v175, v111, v130
	v_cvt_pk_bf16_f32 v130, v106, v107
	v_cvt_pk_bf16_f32 v131, v108, v109
	ds_read_b64_tr_b16 v[106:107], v174 offset:39936
	ds_read_b64_tr_b16 v[108:109], v174 offset:40448
	s_waitcnt lgkmcnt(8)
	v_mfma_f32_32x32x16_bf16 v[66:81], v[166:169], v[146:149], v[66:81]
	v_add_f32_e32 v132, v112, v175
	v_add_f32_e32 v132, v113, v132
	v_add_f32_e32 v162, 0, v132
	v_cvt_pk_bf16_f32 v132, v110, v111
	v_cvt_pk_bf16_f32 v133, v112, v113
	s_add_i32 m0, s60, s33
	s_add_u32 s6, s77, 0xa0000
	s_addc_u32 s7, s78, 0
	global_load_lds_dwordx4 v206, s[6:7]
	s_add_i32 s14, s53, s57
	s_mov_b32 m0, s14
	s_add_u32 s6, s75, 0x22060000
	s_addc_u32 s7, s76, 0
	global_load_lds_dwordx4 v207, s[6:7]
	s_add_u32 s12, s75, 0x22060080
	s_addc_u32 s13, s76, 0
	s_addk_i32 s14, 0x2000
	s_mov_b32 m0, s14
	s_cmp_ge_i32 s79, s55
	s_cselect_b64 s[60:61], -1, 0
	s_cmp_lt_i32 s79, s48
	s_cselect_b64 s[6:7], -1, 0
	global_load_lds_dwordx4 v207, s[12:13]
	s_and_b64 s[60:61], s[60:61], s[6:7]
	s_andn2_b64 vcc, exec, s[60:61]
	s_cbranch_vccnz .LBB0_1162
	ds_read2_b32 v[110:111], v179 offset0:64 offset1:65
	ds_read2_b32 v[112:113], v179 offset0:66 offset1:67
	ds_read2_b32 v[164:165], v179 offset0:72 offset1:73
	ds_read2_b32 v[166:167], v179 offset0:74 offset1:75
	ds_read2_b32 v[168:169], v179 offset0:80 offset1:81
	ds_read2_b32 v[176:177], v179 offset0:82 offset1:83
	ds_read2_b32 v[180:181], v179 offset0:88 offset1:89
	ds_read2_b32 v[210:211], v179 offset0:90 offset1:91
	ds_read2_b32 v[212:213], v179 offset0:96 offset1:97
	ds_read2_b32 v[214:215], v179 offset0:98 offset1:99
	ds_read2_b32 v[216:217], v179 offset0:104 offset1:105
	ds_read2_b32 v[218:219], v179 offset0:106 offset1:107
	s_waitcnt lgkmcnt(11)
	v_pk_add_f32 v[82:83], v[82:83], v[110:111]
	s_waitcnt lgkmcnt(5)
	v_pk_add_f32 v[94:95], v[94:95], v[180:181]
	v_pk_add_f32 v[92:93], v[92:93], v[176:177]
	v_pk_add_f32 v[90:91], v[90:91], v[168:169]
	ds_read2_b32 v[110:111], v179 offset0:112 offset1:113
	ds_read2_b32 v[168:169], v179 offset0:114 offset1:115
	ds_read2_b32 v[176:177], v179 offset0:120 offset1:121
	ds_read2_b32 v[180:181], v179 offset0:122 offset1:123
	s_waitcnt lgkmcnt(8)
	v_pk_add_f32 v[96:97], v[96:97], v[210:211]
	v_pk_add_f32 v[88:89], v[88:89], v[166:167]
	v_pk_add_f32 v[86:87], v[86:87], v[164:165]
	v_pk_add_f32 v[84:85], v[84:85], v[112:113]
	s_waitcnt lgkmcnt(7)
	v_pk_add_f32 v[66:67], v[66:67], v[212:213]
	s_waitcnt lgkmcnt(0)
	v_pk_add_f32 v[80:81], v[80:81], v[180:181]
	v_pk_add_f32 v[78:79], v[78:79], v[176:177]
	v_pk_add_f32 v[76:77], v[76:77], v[168:169]
	v_pk_add_f32 v[74:75], v[74:75], v[110:111]
	v_pk_add_f32 v[72:73], v[72:73], v[218:219]
	v_pk_add_f32 v[70:71], v[70:71], v[216:217]
	v_pk_add_f32 v[68:69], v[68:69], v[214:215]
